# v17 with code placement tuned: post-attention code +24 B, P1-P3 code +40 B (dead s_nop pads only; no instruction changes)
# speedup vs baseline: 1.0148x; 1.0058x over previous
; #define PG8_STAGE(bufoff, gbase, voff) do { _Pragma("unroll") for (int _i = 0; _i < 2; ++_i) \
;         __builtin_amdgcn_global_load_lds((const unsigned*)((const char*)(gbase) + (voff)[_i]), (LAS unsigned*)(lds + (bufoff) + ldsw + _i * 8192), 16, 0, 0); } while (0)
; #define PG8_WAIT_V(n) asm volatile("s_waitcnt vmcnt(" #n ")" ::: "memory")
; #define PG8_BAR __builtin_amdgcn_s_barrier()
; template <class Epi, class Sched, bool ALIGN_EPI = false, bool SP2 = false>
; __device__ __forceinline__ void gemm_phase(LAS unsigned char* lds, const Gemm g, const Sched& S, const Epi& E) {
;     ...
;     for (int i = 0; i < 2; ++i) { int R, C; stage_rc(tid * 16 + i * 8192, R, C); const int Rb = Epi::PERM ? ((R & ~31) + perm32(R & 31)) : R;
;         voffA[i] = (unsigned)(R * K + C) * 2u; voffB[i] = (unsigned)(Rb * K + C) * 2u; }
;     const size_t kstep = (size_t)(BK * 2);
;     const size_t hstep = (size_t)HALF * K * 2;
;     const size_t tstep = 2 * hstep;
;     const unsigned ldsw = (unsigned)wid * 1024u;
;     const int aoff = lds_byte(wr * 64 + fr, fq * 8), boff = lds_byte(wc * 32 + fr, fq * 8);
;     ...
;     if constexpr (SP2) {
;         PG8_STAGE(PG8_SB(0, 0), cB, voffB); PG8_STAGE(PG8_SB(0, 1), cB + hstep, voffB); PG8_STAGE(PG8_SA(0, 0), cA, voffA); PG8_STAGE(PG8_SA(0, 1), cA + hstep, voffA);
;         if (wr == 1) PG8_BAR;
;         PG8_WAIT_V(2); PG8_BAR;
;         PG8_STAGE(PG8_SB(1, 0), cB + kstep, voffB); PG8_STAGE(PG8_SA(1, 0), cA + kstep, voffA); PG8_STAGE(PG8_SB(1, 1), cB + hstep + kstep, voffB);
;         PG8_WAIT_V(6); PG8_BAR;
.LBB0_140:
	s_lshl_b32 s6, s6, 5
	s_lshl_b32 s5, s7, 13
	s_and_b32 s36, s6, 0x60
	s_mov_b64 s[6:7], 0x80
	s_nop 0
	s_nop 0
	s_nop 0
	s_nop 0
	s_nop 0
	s_nop 0
	s_nop 0
	s_nop 0
	s_nop 0
	s_nop 0
	s_add_i32 m0, s43, 0x18000
	v_lshl_add_u64 v[8:9], v[8:9], 0, s[6:7]
	s_lshl_b32 s37, s36, 7
	s_waitcnt vmcnt(2)
	s_barrier
	global_load_lds_dwordx4 v[8:9], off
	v_lshl_add_u64 v[6:7], v[6:7], 0, s[6:7]
	s_add_i32 m0, s43, 0x1a000
	s_add_i32 s68, s43, 0x8000
	s_add_i32 s69, s43, 0xa000
	global_load_lds_dwordx4 v[6:7], off
	v_lshl_add_u64 v[2:3], v[2:3], 0, s[6:7]
	s_mov_b32 m0, s68
	s_add_u32 s28, s46, 0x80080
	global_load_lds_dwordx4 v[2:3], off
	v_lshl_add_u64 v[2:3], v[4:5], 0, s[6:7]
	s_mov_b32 m0, s69
	s_addc_u32 s29, s47, 0
	global_load_lds_dwordx4 v[2:3], off
	s_add_i32 m0, s43, 0x1c000
	v_lshl_add_u64 v[2:3], s[28:29], 0, v[132:133]
	global_load_lds_dwordx4 v[2:3], off
	v_lshl_add_u64 v[2:3], s[28:29], 0, v[128:129]
	s_add_i32 m0, s43, 0x1e000
	v_lshrrev_b32_e32 v1, 1, v1
	global_load_lds_dwordx4 v[2:3], off
	v_or_b32_e32 v148, s4, v12
	v_and_b32_e32 v2, 24, v1
	v_lshlrev_b32_e32 v1, 6, v148
	v_lshlrev_b32_e32 v3, 1, v2
	s_movk_i32 s4, 0x3c0
	v_lshlrev_b32_e32 v4, 2, v148
	v_and_or_b32 v1, v1, s4, v3
	v_and_b32_e32 v4, 32, v4
	v_bitop3_b32 v4, v1, s5, v4 bitop3:0xde
	v_lshl_or_b32 v1, v12, 6, v3
	v_and_b32_e32 v3, 32, v0
	s_add_u32 s4, s16, s8
	v_bitop3_b32 v150, v1, s37, v3 bitop3:0xde
	s_addc_u32 s5, s17, s9
	v_mov_b32_e32 v1, v133
	v_lshl_add_u64 v[136:137], s[4:5], 0, v[0:1]
	v_lshlrev_b32_e32 v0, 15, v15
	v_and_b32_e32 v0, 0xffff0000, v0
	v_lshl_add_u32 v0, v14, 12, v0
	v_and_b32_e32 v1, 1, v15
	v_lshl_or_b32 v0, v1, 6, v0
	v_lshl_add_u32 v138, v16, 1, v0
	v_lshlrev_b32_e32 v0, 15, v10
	v_and_b32_e32 v0, 0xffff0000, v0
	s_waitcnt vmcnt(6)
	v_lshl_add_u32 v0, v11, 12, v0
	v_and_b32_e32 v1, 1, v10
	s_cmpk_lt_u32 s11, 0x100
	v_lshl_or_b32 v0, v1, 6, v0
	s_sext_i32_i16 s73, s10
	s_cselect_b64 s[8:9], -1, 0
	v_or_b32_e32 v151, s36, v2
	v_mov_b32_e32 v139, v133
	v_lshl_add_u32 v140, v13, 1, v0
	v_mov_b32_e32 v141, v133
	v_mov_b64_e32 v[142:143], 0xb00
	v_mov_b64_e32 v[144:145], 0xaff
	s_add_i32 s70, 0, 0x10000
	s_add_i32 s71, 0, 0x14000
	v_add_u32_e32 v152, 0, v4
	v_mov_b32_e32 v153, 0x358637bd
	s_movk_i32 s72, 0x2c00
	s_barrier
	s_branch .LBB0_143

; #define PG8_STAGE(bufoff, gbase, voff) do { _Pragma("unroll") for (int _i = 0; _i < 2; ++_i) \
;         __builtin_amdgcn_global_load_lds((const unsigned*)((const char*)(gbase) + (voff)[_i]), (LAS unsigned*)(lds + (bufoff) + ldsw + _i * 8192), 16, 0, 0); } while (0)
; #define PG8_LDA(dst, b, h) do { _Pragma("unroll") for (int m = 0; m < 4; ++m) _Pragma("unroll") for (int k = 0; k < 2; ++k) dst[m][k] = *(const LAS bf16x8*)(lds + PG8_SA(b, h) + aoff + m * 2048 + k * 1024); } while (0)
; #define PG8_LDB(dst, b, h) do { _Pragma("unroll") for (int n = 0; n < 2; ++n) _Pragma("unroll") for (int k = 0; k < 2; ++k) dst[n][k] = *(const LAS bf16x8*)(lds + PG8_SB(b, h) + boff + n * 2048 + k * 1024); } while (0)
; #define PG8_MMA(ai, bj, At, Bt) do { __builtin_amdgcn_s_setprio(1); _Pragma("unroll") for (int m = 0; m < 4; ++m) _Pragma("unroll") for (int n = 0; n < 2; ++n) _Pragma("unroll") for (int k = 0; k < 2; ++k) \
;         acc[ai][bj][m][n] = __builtin_amdgcn_mfma_f32_16x16x32_bf16(Bt[n][k], At[m][k], acc[ai][bj][m][n], 0, 0, 0); __builtin_amdgcn_s_setprio(0); } while (0)
; #define PG8_WAIT_V(n) asm volatile("s_waitcnt vmcnt(" #n ")" ::: "memory")
; #define PG8_WAIT_L(n) asm volatile("s_waitcnt lgkmcnt(" #n ")" ::: "memory")
; #define PG8_BAR __builtin_amdgcn_s_barrier()
; #define PG8_SCHED __builtin_amdgcn_sched_barrier(0)
; template <class Epi, class Sched, bool ALIGN_EPI = false, bool SP2 = false>
; __device__ __forceinline__ void gemm_phase(LAS unsigned char* lds, const Gemm g, const Sched& S, const Epi& E) {
;     ...
;             if constexpr (SP2) {
;             PG8_LDB(B0, 0, 0); PG8_LDB(B1, 0, 1); PG8_SCHED; PG8_LDA(At, 0, 0); PG8_STAGE(PG8_SA(1, 1), a1 + hstep, voffA);
;             PG8_WAIT_V(8); PG8_WAIT_L(0); PG8_BAR; PG8_MMA(0, 0, At, B0); PG8_MMA(0, 1, At, B1); PG8_BAR; PG8_SCHED;
;             PG8_LDA(At, 0, 1); PG8_STAGE(PG8_SB(0, 0), b2, voffB); PG8_STAGE(PG8_SB(0, 1), b2 + hstep, voffB); PG8_STAGE(PG8_SA(0, 0), a2, voffA);
;             PG8_WAIT_V(8); PG8_WAIT_L(0); PG8_BAR; PG8_MMA(1, 0, At, B0); PG8_MMA(1, 1, At, B1); PG8_BAR; PG8_SCHED;
.LBB0_369:
	ds_read_b128 v[144:147], v167
	ds_read_b128 v[148:151], v167 offset:1024
	ds_read_b128 v[152:155], v167 offset:2048
	ds_read_b128 v[156:159], v167 offset:3072
	ds_read_b128 v[160:163], v168
	ds_read_b128 v[172:175], v168 offset:1024
	ds_read_b128 v[178:181], v168 offset:2048
	ds_read_b128 v[182:185], v168 offset:3072
	s_add_u32 s66, s64, 0xfff80080
	s_addc_u32 s67, s65, -1
	s_cmp_eq_u32 s96, 28
	s_cselect_b32 s69, s16, s67
	s_cselect_b32 s68, s17, s66
	s_cselect_b32 s67, s45, s95
	s_cselect_b32 s66, s47, s94
	s_add_i32 m0, s63, 0xc000
	ds_read_b128 v[190:193], v169
	ds_read_b128 v[194:197], v169 offset:1024
	ds_read_b128 v[198:201], v169 offset:2048
	ds_read_b128 v[202:205], v169 offset:3072
	ds_read_b128 v[206:209], v169 offset:4096
	ds_read_b128 v[210:213], v169 offset:5120
	ds_read_b128 v[214:217], v169 offset:6144
	ds_read_b128 v[218:221], v169 offset:7168
	global_load_lds_dwordx4 v136, s[64:65]
	s_add_i32 m0, s63, 0xe000
	s_nop 0
	global_load_lds_dwordx4 v138, s[64:65]
	s_waitcnt vmcnt(8)
	s_waitcnt lgkmcnt(0)
	s_setprio 1
	s_barrier
	v_mfma_f32_16x16x32_bf16 v[124:127], v[144:147], v[190:193], v[124:127]
	v_mfma_f32_16x16x32_bf16 v[120:123], v[152:155], v[190:193], v[120:123]
	v_mfma_f32_16x16x32_bf16 v[116:119], v[144:147], v[198:201], v[116:119]
	v_mfma_f32_16x16x32_bf16 v[112:115], v[152:155], v[198:201], v[112:115]
	v_mfma_f32_16x16x32_bf16 v[108:111], v[144:147], v[206:209], v[108:111]
	v_mfma_f32_16x16x32_bf16 v[100:103], v[152:155], v[206:209], v[100:103]
	v_mfma_f32_16x16x32_bf16 v[80:83], v[144:147], v[214:217], v[80:83]
	v_mfma_f32_16x16x32_bf16 v[72:75], v[152:155], v[214:217], v[72:75]
	v_mfma_f32_16x16x32_bf16 v[124:127], v[148:151], v[194:197], v[124:127]
	v_mfma_f32_16x16x32_bf16 v[120:123], v[156:159], v[194:197], v[120:123]
	v_mfma_f32_16x16x32_bf16 v[116:119], v[148:151], v[202:205], v[116:119]
	v_mfma_f32_16x16x32_bf16 v[112:115], v[156:159], v[202:205], v[112:115]
	v_mfma_f32_16x16x32_bf16 v[108:111], v[148:151], v[210:213], v[108:111]
	v_mfma_f32_16x16x32_bf16 v[100:103], v[156:159], v[210:213], v[100:103]
	v_mfma_f32_16x16x32_bf16 v[80:83], v[148:151], v[218:221], v[80:83]
	v_mfma_f32_16x16x32_bf16 v[72:75], v[156:159], v[218:221], v[72:75]
	v_mfma_f32_16x16x32_bf16 v[104:107], v[160:163], v[190:193], v[104:107]
	v_mfma_f32_16x16x32_bf16 v[96:99], v[178:181], v[190:193], v[96:99]
	v_mfma_f32_16x16x32_bf16 v[92:95], v[160:163], v[198:201], v[92:95]
	v_mfma_f32_16x16x32_bf16 v[88:91], v[178:181], v[198:201], v[88:91]
	v_mfma_f32_16x16x32_bf16 v[84:87], v[160:163], v[206:209], v[84:87]
	v_mfma_f32_16x16x32_bf16 v[76:79], v[178:181], v[206:209], v[76:79]
	v_mfma_f32_16x16x32_bf16 v[68:71], v[160:163], v[214:217], v[68:71]
	v_mfma_f32_16x16x32_bf16 v[64:67], v[178:181], v[214:217], v[64:67]
	v_mfma_f32_16x16x32_bf16 v[104:107], v[172:175], v[194:197], v[104:107]
	v_mfma_f32_16x16x32_bf16 v[96:99], v[182:185], v[194:197], v[96:99]
	v_mfma_f32_16x16x32_bf16 v[92:95], v[172:175], v[202:205], v[92:95]
	v_mfma_f32_16x16x32_bf16 v[88:91], v[182:185], v[202:205], v[88:91]
	v_mfma_f32_16x16x32_bf16 v[84:87], v[172:175], v[210:213], v[84:87]
	v_mfma_f32_16x16x32_bf16 v[76:79], v[182:185], v[210:213], v[76:79]
	v_mfma_f32_16x16x32_bf16 v[68:71], v[172:175], v[218:221], v[68:71]
	v_mfma_f32_16x16x32_bf16 v[64:67], v[182:185], v[218:221], v[64:67]
	s_setprio 0
	s_barrier
	s_add_u32 s100, s68, 0x80
	s_addc_u32 s101, s69, 0
	s_add_u32 s98, s66, 0x80
	s_addc_u32 s99, s67, 0
	s_add_i32 s74, s87, s70
	s_mov_b32 m0, s74
	ds_read_b128 v[190:193], v169 offset:16384
	ds_read_b128 v[194:197], v169 offset:17408
	ds_read_b128 v[198:201], v169 offset:18432
	ds_read_b128 v[202:205], v169 offset:19456
	ds_read_b128 v[206:209], v169 offset:20480
	ds_read_b128 v[210:213], v169 offset:21504
	ds_read_b128 v[214:217], v169 offset:22528
	ds_read_b128 v[218:221], v169 offset:23552
	global_load_lds_dwordx4 v130, s[66:67]
	s_add_i32 m0, s74, 0x2000
	s_add_u32 vcc_lo, s66, 0x80000
	s_addc_u32 vcc_hi, s67, 0
	s_add_i32 s74, s88, s70
	global_load_lds_dwordx4 v134, s[66:67]
	s_mov_b32 m0, s74
	s_nop 0
	global_load_lds_dwordx4 v130, vcc
	s_add_i32 m0, s74, 0x2000
	s_nop 0
	global_load_lds_dwordx4 v134, vcc
	s_mov_b32 m0, s63
	s_nop 0
	global_load_lds_dwordx4 v128, s[68:69]
	s_mov_b32 m0, s71
	s_nop 0
	global_load_lds_dwordx4 v132, s[68:69]
	s_waitcnt vmcnt(8)
	s_waitcnt lgkmcnt(0)
	s_setprio 1
	s_barrier
	v_mfma_f32_16x16x32_bf16 v[60:63], v[144:147], v[190:193], v[60:63]
	v_mfma_f32_16x16x32_bf16 v[56:59], v[152:155], v[190:193], v[56:59]
	v_mfma_f32_16x16x32_bf16 v[48:51], v[144:147], v[198:201], v[48:51]
	v_mfma_f32_16x16x32_bf16 v[40:43], v[152:155], v[198:201], v[40:43]
	v_mfma_f32_16x16x32_bf16 v[32:35], v[144:147], v[206:209], v[32:35]
	v_mfma_f32_16x16x32_bf16 v[24:27], v[152:155], v[206:209], v[24:27]
	v_mfma_f32_16x16x32_bf16 v[16:19], v[144:147], v[214:217], v[16:19]
	v_mfma_f32_16x16x32_bf16 v[8:11], v[152:155], v[214:217], v[8:11]
	v_mfma_f32_16x16x32_bf16 v[60:63], v[148:151], v[194:197], v[60:63]
	v_mfma_f32_16x16x32_bf16 v[56:59], v[156:159], v[194:197], v[56:59]
	v_mfma_f32_16x16x32_bf16 v[48:51], v[148:151], v[202:205], v[48:51]
	v_mfma_f32_16x16x32_bf16 v[40:43], v[156:159], v[202:205], v[40:43]
	v_mfma_f32_16x16x32_bf16 v[32:35], v[148:151], v[210:213], v[32:35]
	v_mfma_f32_16x16x32_bf16 v[24:27], v[156:159], v[210:213], v[24:27]
	v_mfma_f32_16x16x32_bf16 v[16:19], v[148:151], v[218:221], v[16:19]
	v_mfma_f32_16x16x32_bf16 v[8:11], v[156:159], v[218:221], v[8:11]
	v_mfma_f32_16x16x32_bf16 v[52:55], v[160:163], v[190:193], v[52:55]
	v_mfma_f32_16x16x32_bf16 v[44:47], v[178:181], v[190:193], v[44:47]
	v_mfma_f32_16x16x32_bf16 v[36:39], v[160:163], v[198:201], v[36:39]
	v_mfma_f32_16x16x32_bf16 v[28:31], v[178:181], v[198:201], v[28:31]
	v_mfma_f32_16x16x32_bf16 v[20:23], v[160:163], v[206:209], v[20:23]
	v_mfma_f32_16x16x32_bf16 v[12:15], v[178:181], v[206:209], v[12:15]
	v_mfma_f32_16x16x32_bf16 v[4:7], v[160:163], v[214:217], v[4:7]
	v_mfma_f32_16x16x32_bf16 v[0:3], v[178:181], v[214:217], v[0:3]
	v_mfma_f32_16x16x32_bf16 v[52:55], v[172:175], v[194:197], v[52:55]
	v_mfma_f32_16x16x32_bf16 v[44:47], v[182:185], v[194:197], v[44:47]
	v_mfma_f32_16x16x32_bf16 v[36:39], v[172:175], v[202:205], v[36:39]
	v_mfma_f32_16x16x32_bf16 v[28:31], v[182:185], v[202:205], v[28:31]
	v_mfma_f32_16x16x32_bf16 v[20:23], v[172:175], v[210:213], v[20:23]
	v_mfma_f32_16x16x32_bf16 v[12:15], v[182:185], v[210:213], v[12:15]
	v_mfma_f32_16x16x32_bf16 v[4:7], v[172:175], v[218:221], v[4:7]
	v_mfma_f32_16x16x32_bf16 v[0:3], v[182:185], v[218:221], v[0:3]
	s_setprio 0
	s_barrier
; #define PG8_STAGE(bufoff, gbase, voff) do { _Pragma("unroll") for (int _i = 0; _i < 2; ++_i) \
;         __builtin_amdgcn_global_load_lds((const unsigned*)((const char*)(gbase) + (voff)[_i]), (LAS unsigned*)(lds + (bufoff) + ldsw + _i * 8192), 16, 0, 0); } while (0)
; #define PG8_LDA(dst, b, h) do { _Pragma("unroll") for (int m = 0; m < 4; ++m) _Pragma("unroll") for (int k = 0; k < 2; ++k) dst[m][k] = *(const LAS bf16x8*)(lds + PG8_SA(b, h) + aoff + m * 2048 + k * 1024); } while (0)
; #define PG8_LDB(dst, b, h) do { _Pragma("unroll") for (int n = 0; n < 2; ++n) _Pragma("unroll") for (int k = 0; k < 2; ++k) dst[n][k] = *(const LAS bf16x8*)(lds + PG8_SB(b, h) + boff + n * 2048 + k * 1024); } while (0)
; #define PG8_MMA(ai, bj, At, Bt) do { __builtin_amdgcn_s_setprio(1); _Pragma("unroll") for (int m = 0; m < 4; ++m) _Pragma("unroll") for (int n = 0; n < 2; ++n) _Pragma("unroll") for (int k = 0; k < 2; ++k) \
;         acc[ai][bj][m][n] = __builtin_amdgcn_mfma_f32_16x16x32_bf16(Bt[n][k], At[m][k], acc[ai][bj][m][n], 0, 0, 0); __builtin_amdgcn_s_setprio(0); } while (0)
; #define PG8_WAIT_V(n) asm volatile("s_waitcnt vmcnt(" #n ")" ::: "memory")
; #define PG8_WAIT_L(n) asm volatile("s_waitcnt lgkmcnt(" #n ")" ::: "memory")
; #define PG8_BAR __builtin_amdgcn_s_barrier()
; #define PG8_SCHED __builtin_amdgcn_sched_barrier(0)
; template <class Epi, class Sched, bool ALIGN_EPI = false, bool SP2 = false>
; __device__ __forceinline__ void gemm_phase(LAS unsigned char* lds, const Gemm g, const Sched& S, const Epi& E) {
;     ...
;         for (int t = 0; t < nt; t += 2) {
;             const bool last = (t == nt - 2);
;             const char* a1 = cA + (size_t)(t + 1) * kstep;
;             const char* a2 = last ? nA : cA + (size_t)(t + 2) * kstep; const char* b2 = last ? nB : cB + (size_t)(t + 2) * kstep;
;     ...
;             PG8_LDB(B0, 1, 0); PG8_LDB(B1, 1, 1); PG8_SCHED; PG8_LDA(At, 1, 0); PG8_STAGE(PG8_SA(0, 1), a2 + hstep, voffA);
;             PG8_WAIT_V(8); PG8_WAIT_L(0); PG8_BAR; PG8_MMA(0, 0, At, B0); PG8_MMA(0, 1, At, B1); PG8_BAR; PG8_SCHED;
;             PG8_LDA(At, 1, 1); PG8_STAGE(PG8_SB(1, 0), b3, voffB); PG8_STAGE(PG8_SB(1, 1), b3 + hstep, voffB); PG8_STAGE(PG8_SA(1, 0), a3, voffA);
;             PG8_WAIT_V(8); PG8_WAIT_L(0); PG8_BAR; PG8_MMA(1, 0, At, B0); PG8_MMA(1, 1, At, B1); PG8_BAR; PG8_SCHED;
	s_add_i32 s74, 0, 0x18000
	s_add_i32 s97, 0, 0x1c000
	v_add_u32_e32 v156, s74, v165
	v_add_u32_e32 v171, s97, v165
	ds_read_b128 v[144:147], v156
	ds_read_b128 v[148:151], v156 offset:1024
	ds_read_b128 v[152:155], v156 offset:2048
	ds_read_b128 v[156:159], v156 offset:3072
	ds_read_b128 v[160:163], v171
	ds_read_b128 v[172:175], v171 offset:1024
	ds_read_b128 v[178:181], v171 offset:2048
	ds_read_b128 v[182:185], v171 offset:3072
	s_add_u32 s68, s68, 0x80000
	s_addc_u32 s69, s69, 0
	s_mov_b32 m0, s72
	ds_read_b128 v[190:193], v169 offset:32768
	ds_read_b128 v[194:197], v169 offset:33792
	ds_read_b128 v[198:201], v169 offset:34816
	ds_read_b128 v[202:205], v169 offset:35840
	ds_read_b128 v[206:209], v169 offset:36864
	ds_read_b128 v[210:213], v169 offset:37888
	ds_read_b128 v[214:217], v169 offset:38912
	ds_read_b128 v[218:221], v169 offset:39936
	global_load_lds_dwordx4 v128, s[68:69]
	s_mov_b32 m0, s73
	s_nop 0
	global_load_lds_dwordx4 v132, s[68:69]
	s_waitcnt vmcnt(8)
	s_waitcnt lgkmcnt(0)
	s_setprio 1
	s_barrier
	v_mfma_f32_16x16x32_bf16 v[124:127], v[144:147], v[190:193], v[124:127]
	v_mfma_f32_16x16x32_bf16 v[120:123], v[152:155], v[190:193], v[120:123]
	v_mfma_f32_16x16x32_bf16 v[116:119], v[144:147], v[198:201], v[116:119]
	v_mfma_f32_16x16x32_bf16 v[112:115], v[152:155], v[198:201], v[112:115]
	v_mfma_f32_16x16x32_bf16 v[108:111], v[144:147], v[206:209], v[108:111]
	v_mfma_f32_16x16x32_bf16 v[100:103], v[152:155], v[206:209], v[100:103]
	v_mfma_f32_16x16x32_bf16 v[80:83], v[144:147], v[214:217], v[80:83]
	v_mfma_f32_16x16x32_bf16 v[72:75], v[152:155], v[214:217], v[72:75]
	v_mfma_f32_16x16x32_bf16 v[124:127], v[148:151], v[194:197], v[124:127]
	v_mfma_f32_16x16x32_bf16 v[120:123], v[156:159], v[194:197], v[120:123]
	v_mfma_f32_16x16x32_bf16 v[116:119], v[148:151], v[202:205], v[116:119]
	v_mfma_f32_16x16x32_bf16 v[112:115], v[156:159], v[202:205], v[112:115]
	v_mfma_f32_16x16x32_bf16 v[108:111], v[148:151], v[210:213], v[108:111]
	v_mfma_f32_16x16x32_bf16 v[100:103], v[156:159], v[210:213], v[100:103]
	v_mfma_f32_16x16x32_bf16 v[80:83], v[148:151], v[218:221], v[80:83]
	v_mfma_f32_16x16x32_bf16 v[72:75], v[156:159], v[218:221], v[72:75]
	v_mfma_f32_16x16x32_bf16 v[104:107], v[160:163], v[190:193], v[104:107]
	v_mfma_f32_16x16x32_bf16 v[96:99], v[178:181], v[190:193], v[96:99]
	v_mfma_f32_16x16x32_bf16 v[92:95], v[160:163], v[198:201], v[92:95]
	v_mfma_f32_16x16x32_bf16 v[88:91], v[178:181], v[198:201], v[88:91]
	v_mfma_f32_16x16x32_bf16 v[84:87], v[160:163], v[206:209], v[84:87]
	v_mfma_f32_16x16x32_bf16 v[76:79], v[178:181], v[206:209], v[76:79]
	v_mfma_f32_16x16x32_bf16 v[68:71], v[160:163], v[214:217], v[68:71]
	v_mfma_f32_16x16x32_bf16 v[64:67], v[178:181], v[214:217], v[64:67]
	v_mfma_f32_16x16x32_bf16 v[104:107], v[172:175], v[194:197], v[104:107]
	v_mfma_f32_16x16x32_bf16 v[96:99], v[182:185], v[194:197], v[96:99]
	v_mfma_f32_16x16x32_bf16 v[92:95], v[172:175], v[202:205], v[92:95]
	v_mfma_f32_16x16x32_bf16 v[88:91], v[182:185], v[202:205], v[88:91]
	v_mfma_f32_16x16x32_bf16 v[84:87], v[172:175], v[210:213], v[84:87]
	v_mfma_f32_16x16x32_bf16 v[76:79], v[182:185], v[210:213], v[76:79]
	v_mfma_f32_16x16x32_bf16 v[68:71], v[172:175], v[218:221], v[68:71]
	v_mfma_f32_16x16x32_bf16 v[64:67], v[182:185], v[218:221], v[64:67]
	s_setprio 0
	s_barrier
	s_add_i32 s68, s74, s70
	s_mov_b32 m0, s68
	ds_read_b128 v[190:193], v169 offset:49152
	ds_read_b128 v[194:197], v169 offset:50176
	ds_read_b128 v[198:201], v169 offset:51200
	ds_read_b128 v[202:205], v169 offset:52224
	ds_read_b128 v[206:209], v169 offset:53248
	ds_read_b128 v[210:213], v169 offset:54272
	ds_read_b128 v[214:217], v169 offset:55296
	ds_read_b128 v[218:221], v169 offset:56320
	global_load_lds_dwordx4 v130, s[98:99]
	s_add_i32 m0, s68, 0x2000
	s_add_u32 s66, s66, 0x80080
	s_addc_u32 s67, s67, 0
	s_add_i32 s68, s97, s70
	global_load_lds_dwordx4 v134, s[98:99]
	s_mov_b32 m0, s68
	s_nop 0
	global_load_lds_dwordx4 v130, s[66:67]
	s_add_i32 m0, s68, 0x2000
	s_nop 0
	global_load_lds_dwordx4 v134, s[66:67]
	s_mov_b32 m0, s85
	s_nop 0
	global_load_lds_dwordx4 v128, s[100:101]
	s_mov_b32 m0, s86
	s_nop 0
	global_load_lds_dwordx4 v132, s[100:101]
	s_waitcnt vmcnt(8)
	s_waitcnt lgkmcnt(0)
	s_setprio 1
	s_barrier
	v_mfma_f32_16x16x32_bf16 v[60:63], v[144:147], v[190:193], v[60:63]
	v_mfma_f32_16x16x32_bf16 v[56:59], v[152:155], v[190:193], v[56:59]
	v_mfma_f32_16x16x32_bf16 v[48:51], v[144:147], v[198:201], v[48:51]
	v_mfma_f32_16x16x32_bf16 v[40:43], v[152:155], v[198:201], v[40:43]
	v_mfma_f32_16x16x32_bf16 v[32:35], v[144:147], v[206:209], v[32:35]
	v_mfma_f32_16x16x32_bf16 v[24:27], v[152:155], v[206:209], v[24:27]
	v_mfma_f32_16x16x32_bf16 v[16:19], v[144:147], v[214:217], v[16:19]
	v_mfma_f32_16x16x32_bf16 v[8:11], v[152:155], v[214:217], v[8:11]
	v_mfma_f32_16x16x32_bf16 v[60:63], v[148:151], v[194:197], v[60:63]
	v_mfma_f32_16x16x32_bf16 v[56:59], v[156:159], v[194:197], v[56:59]
	v_mfma_f32_16x16x32_bf16 v[48:51], v[148:151], v[202:205], v[48:51]
	v_mfma_f32_16x16x32_bf16 v[40:43], v[156:159], v[202:205], v[40:43]
	v_mfma_f32_16x16x32_bf16 v[32:35], v[148:151], v[210:213], v[32:35]
	v_mfma_f32_16x16x32_bf16 v[24:27], v[156:159], v[210:213], v[24:27]
	v_mfma_f32_16x16x32_bf16 v[16:19], v[148:151], v[218:221], v[16:19]
	v_mfma_f32_16x16x32_bf16 v[8:11], v[156:159], v[218:221], v[8:11]
	v_mfma_f32_16x16x32_bf16 v[52:55], v[160:163], v[190:193], v[52:55]
	v_mfma_f32_16x16x32_bf16 v[44:47], v[178:181], v[190:193], v[44:47]
	v_mfma_f32_16x16x32_bf16 v[36:39], v[160:163], v[198:201], v[36:39]
	v_mfma_f32_16x16x32_bf16 v[28:31], v[178:181], v[198:201], v[28:31]
	v_mfma_f32_16x16x32_bf16 v[20:23], v[160:163], v[206:209], v[20:23]
	v_mfma_f32_16x16x32_bf16 v[12:15], v[178:181], v[206:209], v[12:15]
	v_mfma_f32_16x16x32_bf16 v[4:7], v[160:163], v[214:217], v[4:7]
	v_mfma_f32_16x16x32_bf16 v[0:3], v[178:181], v[214:217], v[0:3]
	v_mfma_f32_16x16x32_bf16 v[52:55], v[172:175], v[194:197], v[52:55]
	v_mfma_f32_16x16x32_bf16 v[44:47], v[182:185], v[194:197], v[44:47]
	v_mfma_f32_16x16x32_bf16 v[36:39], v[172:175], v[202:205], v[36:39]
	v_mfma_f32_16x16x32_bf16 v[28:31], v[182:185], v[202:205], v[28:31]
	v_mfma_f32_16x16x32_bf16 v[20:23], v[172:175], v[210:213], v[20:23]
	v_mfma_f32_16x16x32_bf16 v[12:15], v[182:185], v[210:213], v[12:15]
	v_mfma_f32_16x16x32_bf16 v[4:7], v[172:175], v[218:221], v[4:7]
	v_mfma_f32_16x16x32_bf16 v[0:3], v[182:185], v[218:221], v[0:3]
	s_setprio 0
	s_barrier
	s_add_i32 s96, s96, 2
	s_add_u32 s64, s64, 0x100
	s_addc_u32 s65, s65, 0
	s_add_u32 s94, s94, 0x100
	s_addc_u32 s95, s95, 0
	s_cmp_gt_u32 s96, 29
	s_cbranch_scc0 .LBB0_369
	s_branch .Lsapad1
	s_nop 0
	s_nop 0
	s_nop 0
	s_nop 0
	s_nop 0
	s_nop 0
	s_nop 0
	s_nop 0
	s_nop 0
	s_nop 0
	s_nop 0
	s_nop 0
	s_nop 0
	s_nop 0
	s_nop 0
	s_nop 0
	s_nop 0
	s_nop 0
	s_nop 0
	s_nop 0
	s_nop 0
	s_nop 0
	s_nop 0
	s_nop 0
	s_nop 0
	s_nop 0
.Lsapad1:
	s_and_b64 vcc, exec, s[10:11]
	s_cbranch_vccz .LBB0_372
	s_barrier

; template <int WIN> __device__ __forceinline__ void pooled_tile(const bf16_t* __restrict__ UB, bf16_t* __restrict__ PL, int g, int pm, int tidp) {
; #pragma unroll 1
;     for (int pass = 0; pass < 2; ++pass) {
;         const int chunk = tidp & 31, seg = (tidp >> 5) + 16 * pass;
;         const int r0 = pm * 256 + seg * 8, sq0 = r0 & (SEQ - 1);
;         const bf16_t* up = UB + (size_t)r0 * AW + g * 256 + chunk * 8;
; __global__ void __launch_bounds__(NWAVES * 64, 2) fwd_kernel(Args args) {
;     ...
;         int tidp = threadIdx.x; asm volatile("" : "+v"(tidp));
;         for (int L = bx; L < 256; L += G) {
;             const int g = L >> 6, pm = L & 63;
;             if (g == 0) pooled_tile<2>(UB, PL, g, pm, tidp); else if (g == 1) pooled_tile<4>(UB, PL, g, pm, tidp); else if (g == 2) pooled_tile<8>(UB, PL, g, pm, tidp); else pooled_tile<16>(UB, PL, g, pm, tidp);
.LBB0_473:
	s_nop 0
	s_nop 0
	s_nop 0
	s_nop 0
	s_nop 0
	s_nop 0
	v_mov_b32_e32 v0, v177
	s_andn2_b64 vcc, exec, s[36:37]
	s_cbranch_vccnz .LBB0_555
	v_ashrrev_i32_e32 v1, 2, v0
	v_lshlrev_b32_e32 v0, 4, v0
	s_add_u32 s8, s54, 0x15d04000
	v_and_b32_e32 v144, 0x1f0, v0
	v_mov_b32_e32 v145, 0
	s_addc_u32 s9, s55, 0
	v_and_b32_e32 v154, -8, v1
	v_lshl_add_u64 v[0:1], s[54:55], 0, v[144:145]
	s_mov_b64 s[0:1], 0x11d04000
	s_lshl_b64 s[28:29], s[2:3], 9
	v_lshl_add_u64 v[146:147], s[8:9], 0, v[144:145]
	v_lshl_add_u64 v[148:149], v[0:1], 0, s[0:1]
	s_bitset1_b32 s28, 8
	s_lshl_b64 s[36:37], s[24:25], 9
	s_mov_b64 s[38:39], 0x400
	s_movk_i32 s15, 0x1000
	s_movk_i32 s35, 0x2000
	s_movk_i32 s66, 0x3000
	s_mov_b32 s67, 0x1000000
	s_mov_b32 s68, 0x3e000000
	s_mov_b64 s[40:41], 0x200
	s_mov_b32 s69, 0x800000
	s_mov_b32 s70, 0x3e800000
	s_mov_b32 s71, 0x7fffffe0
	s_mov_b64 s[42:43], 0x80
	s_movk_i32 s72, 0x3c0
	s_mov_b64 s[44:45], 0x80000
	s_mov_b64 s[46:47], 0x90000
	s_mov_b64 s[48:49], 0xa0000
	s_mov_b64 s[50:51], 0xb0000
	v_mov_b32_e32 v155, 1
	s_mov_b32 s73, s2
	s_branch .LBB0_476
